# speedup vs baseline: 1.0280x; 1.0280x over previous
; #define LAS __attribute__((address_space(3)))
; __device__ __forceinline__ bf16_t f2bf(float f) { return (bf16_t)(pk_bf16(f, 0.f) & 0xffffu); }
; __device__ __forceinline__ int crow(int reg, int h) { return (reg & 3) + 8 * (reg >> 2) + 4 * h; }
; template <int DQK, int DV, int MODE> ...
;     ...
;     __builtin_amdgcn_s_setprio(0);
;     l += __shfl_xor(l, 32);
;     if (h == 0) wsf[r] = 1.0f / l;
;     f32x4 a4[4];
; #pragma unroll
;     for (int g = 0; g < 4; ++g) a4[g] = *(const LAS f32x4*)(wsf + 8 * g + 4 * h);
;     bf16_t* op = Ob + (size_t)(qrow_base + wid * 32) * DM + ((MODE == 2) ? hd * 64 : hd * 128) + r;
; #pragma unroll
;     for (int d = 0; d < DV / 32; ++d)
; #pragma unroll
;         for (int e = 0; e < 16; ++e) op[(size_t)crow(e, h) * DM + 32 * d] = f2bf(o[d][e] * a4[e >> 2][e & 3]);
.LBB0_589:
	s_or_b64 exec, exec, s[38:39]
	v_mov_b32_e32 v173, v169
	v_or_b32_e32 v174, 0x1000, v172
	v_mov_b32_e32 v175, v169
	v_or_b32_e32 v176, 0x2000, v172
	v_mov_b32_e32 v177, v169
	v_or_b32_e32 v178, 0x3000, v172
	v_mov_b32_e32 v179, v169
	v_or_b32_e32 v180, 0x8000, v172
	v_mov_b32_e32 v181, v169
	v_or_b32_e32 v182, 0x9000, v172
	v_mov_b32_e32 v183, v169
	v_or_b32_e32 v184, 0xa000, v172
	v_mov_b32_e32 v185, v169
	v_or_b32_e32 v186, 0xb000, v172
	v_mov_b32_e32 v187, v169
	v_or_b32_e32 v188, 0x10000, v172
	v_mov_b32_e32 v189, v169
	v_or_b32_e32 v190, 0x11000, v172
	v_mov_b32_e32 v191, v169
	v_or_b32_e32 v192, 0x12000, v172
	v_mov_b32_e32 v193, v169
	v_or_b32_e32 v194, 0x13000, v172
	v_mov_b32_e32 v195, v169
	v_or_b32_e32 v196, 0x18000, v172
	v_mov_b32_e32 v197, v169
	v_or_b32_e32 v198, 0x19000, v172
	v_mov_b32_e32 v199, v169
	v_or_b32_e32 v200, 0x1a000, v172
	v_mov_b32_e32 v201, v169
	v_or_b32_e32 v202, 0x1b000, v172
	v_mov_b32_e32 v203, v169
	s_lshl_b64 s[6:7], s[26:27], 12
	s_add_u32 s6, s78, s6
	s_addc_u32 s7, s79, s7
	ds_read_b128 v[68:71], v219
	ds_read_b128 v[72:75], v219 offset:32
	ds_read_b128 v[76:79], v219 offset:64
	s_waitcnt lgkmcnt(3)
	ds_read_b128 v[64:67], v219 offset:96
	s_add_u32 s6, s6, s0
	s_addc_u32 s7, s7, 0
	v_lshlrev_b32_e32 v80, 1, v166
	v_mov_b32_e32 v81, v169
	v_lshl_add_u64 v[80:81], s[6:7], 0, v[80:81]
	s_waitcnt lgkmcnt(3)
	v_mul_f32_e32 v48, v48, v68
	v_cvt_pk_bf16_f32 v48, v48, s0
	v_lshl_add_u64 v[82:83], v[80:81], 0, v[172:173]
	global_store_short v[82:83], v48, off
	v_mul_f32_e32 v48, v49, v69
	v_cvt_pk_bf16_f32 v84, v48, s0
	v_lshl_add_u64 v[48:49], v[80:81], 0, v[174:175]
	global_store_short v[48:49], v84, off
	v_mul_f32_e32 v48, v50, v70
	v_cvt_pk_bf16_f32 v50, v48, s0
	v_lshl_add_u64 v[48:49], v[80:81], 0, v[176:177]
	global_store_short v[48:49], v50, off
	v_mul_f32_e32 v48, v51, v71
	v_cvt_pk_bf16_f32 v50, v48, s0
	v_lshl_add_u64 v[48:49], v[80:81], 0, v[178:179]
	global_store_short v[48:49], v50, off
	s_waitcnt lgkmcnt(2)
	v_mul_f32_e32 v48, v52, v72
	v_cvt_pk_bf16_f32 v50, v48, s0
	v_lshl_add_u64 v[48:49], v[80:81], 0, v[180:181]
	global_store_short v[48:49], v50, off
	v_mul_f32_e32 v48, v53, v73
	v_cvt_pk_bf16_f32 v50, v48, s0
	v_lshl_add_u64 v[48:49], v[80:81], 0, v[182:183]
	global_store_short v[48:49], v50, off
	v_mul_f32_e32 v48, v54, v74
	v_cvt_pk_bf16_f32 v50, v48, s0
	v_lshl_add_u64 v[48:49], v[80:81], 0, v[184:185]
	global_store_short v[48:49], v50, off
	v_mul_f32_e32 v48, v55, v75
	v_cvt_pk_bf16_f32 v50, v48, s0
	v_lshl_add_u64 v[48:49], v[80:81], 0, v[186:187]
	global_store_short v[48:49], v50, off
	s_waitcnt lgkmcnt(1)
	v_mul_f32_e32 v48, v56, v76
	v_cvt_pk_bf16_f32 v50, v48, s0
	v_lshl_add_u64 v[48:49], v[80:81], 0, v[188:189]
	global_store_short v[48:49], v50, off
	v_mul_f32_e32 v48, v57, v77
	v_cvt_pk_bf16_f32 v50, v48, s0
	v_lshl_add_u64 v[48:49], v[80:81], 0, v[190:191]
	global_store_short v[48:49], v50, off
	v_mul_f32_e32 v48, v58, v78
	v_cvt_pk_bf16_f32 v50, v48, s0
	v_lshl_add_u64 v[48:49], v[80:81], 0, v[192:193]
	global_store_short v[48:49], v50, off
	v_mul_f32_e32 v48, v59, v79
	v_cvt_pk_bf16_f32 v50, v48, s0
	v_lshl_add_u64 v[48:49], v[80:81], 0, v[194:195]
	global_store_short v[48:49], v50, off
	s_waitcnt lgkmcnt(0)
	v_mul_f32_e32 v48, v60, v64
	v_cvt_pk_bf16_f32 v50, v48, s0
	v_lshl_add_u64 v[48:49], v[80:81], 0, v[196:197]
	global_store_short v[48:49], v50, off
	v_mul_f32_e32 v48, v61, v65
	v_cvt_pk_bf16_f32 v50, v48, s0
	v_lshl_add_u64 v[48:49], v[80:81], 0, v[198:199]
	global_store_short v[48:49], v50, off
	v_mul_f32_e32 v48, v62, v66
	v_cvt_pk_bf16_f32 v50, v48, s0
	v_lshl_add_u64 v[48:49], v[80:81], 0, v[200:201]
	global_store_short v[48:49], v50, off
	v_mul_f32_e32 v48, v63, v67
	v_mul_f32_e32 v32, v32, v68
	v_cvt_pk_bf16_f32 v50, v48, s0
	v_lshl_add_u64 v[48:49], v[80:81], 0, v[202:203]
	v_cvt_pk_bf16_f32 v32, v32, s0
	global_store_short v[48:49], v50, off
	v_lshl_add_u64 v[48:49], v[80:81], 0, 64
	global_store_short v[82:83], v32, off offset:64
	v_mul_f32_e32 v32, v33, v69
	v_cvt_pk_bf16_f32 v50, v32, s0
	v_lshl_add_u64 v[32:33], v[48:49], 0, v[174:175]
	global_store_short v[32:33], v50, off
	v_mul_f32_e32 v32, v34, v70
	v_cvt_pk_bf16_f32 v34, v32, s0
	v_lshl_add_u64 v[32:33], v[48:49], 0, v[176:177]
	global_store_short v[32:33], v34, off
	v_mul_f32_e32 v32, v35, v71
	v_cvt_pk_bf16_f32 v34, v32, s0
	v_lshl_add_u64 v[32:33], v[48:49], 0, v[178:179]
	global_store_short v[32:33], v34, off
	v_mul_f32_e32 v32, v36, v72
	v_cvt_pk_bf16_f32 v34, v32, s0
	v_lshl_add_u64 v[32:33], v[48:49], 0, v[180:181]
	global_store_short v[32:33], v34, off
	v_mul_f32_e32 v32, v37, v73
	v_cvt_pk_bf16_f32 v34, v32, s0
	v_lshl_add_u64 v[32:33], v[48:49], 0, v[182:183]
	global_store_short v[32:33], v34, off
	v_mul_f32_e32 v32, v38, v74
	v_cvt_pk_bf16_f32 v34, v32, s0
	v_lshl_add_u64 v[32:33], v[48:49], 0, v[184:185]
	global_store_short v[32:33], v34, off
	v_mul_f32_e32 v32, v39, v75
	v_cvt_pk_bf16_f32 v34, v32, s0
	v_lshl_add_u64 v[32:33], v[48:49], 0, v[186:187]
	global_store_short v[32:33], v34, off
	v_mul_f32_e32 v32, v40, v76
	v_cvt_pk_bf16_f32 v34, v32, s0
	v_lshl_add_u64 v[32:33], v[48:49], 0, v[188:189]
	global_store_short v[32:33], v34, off
	v_mul_f32_e32 v32, v41, v77
	v_cvt_pk_bf16_f32 v34, v32, s0
	v_lshl_add_u64 v[32:33], v[48:49], 0, v[190:191]
	global_store_short v[32:33], v34, off
	v_mul_f32_e32 v32, v42, v78
	v_cvt_pk_bf16_f32 v34, v32, s0
	v_lshl_add_u64 v[32:33], v[48:49], 0, v[192:193]
	global_store_short v[32:33], v34, off
	v_mul_f32_e32 v32, v43, v79
; __device__ __forceinline__ bf16_t f2bf(float f) { return (bf16_t)(pk_bf16(f, 0.f) & 0xffffu); }
; __device__ __forceinline__ int crow(int reg, int h) { return (reg & 3) + 8 * (reg >> 2) + 4 * h; }
; template <int DQK, int DV, int MODE> ...
;     ...
; #pragma unroll
;     for (int d = 0; d < DV / 32; ++d)
; #pragma unroll
;         for (int e = 0; e < 16; ++e) op[(size_t)crow(e, h) * DM + 32 * d] = f2bf(o[d][e] * a4[e >> 2][e & 3]);
;     __syncthreads();
; __global__ void __launch_bounds__(512, 2) mk_fwd(Args args) {
;     ...
;         for (int j = F.vcu; j < 576; j += F.G) { const bool cq = j >= 512; const int jj = cq ? j - 512 : j;
;             flash_unit<192, 128, 0>(F.lds, Qb, KVb, Zb, MIXb, cq ? (jj >> 3) : (jj >> 6), cq ? (jj & 7) : ((jj >> 3) & 7), cq ? 0 : (jj & 7), 0.f, cq); }
	v_cvt_pk_bf16_f32 v34, v32, s0
	v_lshl_add_u64 v[32:33], v[48:49], 0, v[194:195]
	global_store_short v[32:33], v34, off
	v_mul_f32_e32 v32, v44, v64
	v_cvt_pk_bf16_f32 v34, v32, s0
	v_lshl_add_u64 v[32:33], v[48:49], 0, v[196:197]
	global_store_short v[32:33], v34, off
	v_mul_f32_e32 v32, v45, v65
	v_cvt_pk_bf16_f32 v34, v32, s0
	v_lshl_add_u64 v[32:33], v[48:49], 0, v[198:199]
	global_store_short v[32:33], v34, off
	v_mul_f32_e32 v32, v46, v66
	v_cvt_pk_bf16_f32 v34, v32, s0
	v_lshl_add_u64 v[32:33], v[48:49], 0, v[200:201]
	global_store_short v[32:33], v34, off
	v_mul_f32_e32 v32, v47, v67
	v_mul_f32_e32 v16, v16, v68
	v_cvt_pk_bf16_f32 v34, v32, s0
	v_lshl_add_u64 v[32:33], v[48:49], 0, v[202:203]
	v_cvt_pk_bf16_f32 v16, v16, s0
	global_store_short v[32:33], v34, off
	v_lshl_add_u64 v[32:33], v[80:81], 0, s[10:11]
	global_store_short v[82:83], v16, off offset:128
	v_mul_f32_e32 v16, v17, v69
	v_cvt_pk_bf16_f32 v34, v16, s0
	v_lshl_add_u64 v[16:17], v[32:33], 0, v[174:175]
	global_store_short v[16:17], v34, off
	v_mul_f32_e32 v16, v18, v70
	v_cvt_pk_bf16_f32 v18, v16, s0
	v_lshl_add_u64 v[16:17], v[32:33], 0, v[176:177]
	global_store_short v[16:17], v18, off
	v_mul_f32_e32 v16, v19, v71
	v_cvt_pk_bf16_f32 v18, v16, s0
	v_lshl_add_u64 v[16:17], v[32:33], 0, v[178:179]
	global_store_short v[16:17], v18, off
	v_mul_f32_e32 v16, v20, v72
	v_cvt_pk_bf16_f32 v18, v16, s0
	v_lshl_add_u64 v[16:17], v[32:33], 0, v[180:181]
	global_store_short v[16:17], v18, off
	v_mul_f32_e32 v16, v21, v73
	v_cvt_pk_bf16_f32 v18, v16, s0
	v_lshl_add_u64 v[16:17], v[32:33], 0, v[182:183]
	global_store_short v[16:17], v18, off
	v_mul_f32_e32 v16, v22, v74
	v_cvt_pk_bf16_f32 v18, v16, s0
	v_lshl_add_u64 v[16:17], v[32:33], 0, v[184:185]
	global_store_short v[16:17], v18, off
	v_mul_f32_e32 v16, v23, v75
	v_cvt_pk_bf16_f32 v18, v16, s0
	v_lshl_add_u64 v[16:17], v[32:33], 0, v[186:187]
	global_store_short v[16:17], v18, off
	v_mul_f32_e32 v16, v24, v76
	v_cvt_pk_bf16_f32 v18, v16, s0
	v_lshl_add_u64 v[16:17], v[32:33], 0, v[188:189]
	global_store_short v[16:17], v18, off
	v_mul_f32_e32 v16, v25, v77
	v_cvt_pk_bf16_f32 v18, v16, s0
	v_lshl_add_u64 v[16:17], v[32:33], 0, v[190:191]
	global_store_short v[16:17], v18, off
	v_mul_f32_e32 v16, v26, v78
	v_cvt_pk_bf16_f32 v18, v16, s0
	v_lshl_add_u64 v[16:17], v[32:33], 0, v[192:193]
	global_store_short v[16:17], v18, off
	v_mul_f32_e32 v16, v27, v79
	v_cvt_pk_bf16_f32 v18, v16, s0
	v_lshl_add_u64 v[16:17], v[32:33], 0, v[194:195]
	global_store_short v[16:17], v18, off
	v_mul_f32_e32 v16, v28, v64
	v_cvt_pk_bf16_f32 v18, v16, s0
	v_lshl_add_u64 v[16:17], v[32:33], 0, v[196:197]
	global_store_short v[16:17], v18, off
	v_mul_f32_e32 v16, v29, v65
	v_cvt_pk_bf16_f32 v18, v16, s0
	v_lshl_add_u64 v[16:17], v[32:33], 0, v[198:199]
	global_store_short v[16:17], v18, off
	v_mul_f32_e32 v16, v30, v66
	v_cvt_pk_bf16_f32 v18, v16, s0
	v_lshl_add_u64 v[16:17], v[32:33], 0, v[200:201]
	global_store_short v[16:17], v18, off
	v_mul_f32_e32 v16, v31, v67
	v_mul_f32_e32 v0, v0, v68
	v_cvt_pk_bf16_f32 v18, v16, s0
	v_lshl_add_u64 v[16:17], v[32:33], 0, v[202:203]
	v_cvt_pk_bf16_f32 v0, v0, s0
	global_store_short v[16:17], v18, off
	v_lshl_add_u64 v[16:17], v[80:81], 0, s[12:13]
	global_store_short v[82:83], v0, off offset:192
	v_mul_f32_e32 v0, v1, v69
	v_cvt_pk_bf16_f32 v18, v0, s0
	v_lshl_add_u64 v[0:1], v[16:17], 0, v[174:175]
	global_store_short v[0:1], v18, off
	v_mul_f32_e32 v0, v2, v70
	v_cvt_pk_bf16_f32 v2, v0, s0
	v_lshl_add_u64 v[0:1], v[16:17], 0, v[176:177]
	global_store_short v[0:1], v2, off
	v_mul_f32_e32 v0, v3, v71
	v_cvt_pk_bf16_f32 v2, v0, s0
	v_lshl_add_u64 v[0:1], v[16:17], 0, v[178:179]
	global_store_short v[0:1], v2, off
	v_mul_f32_e32 v0, v4, v72
	v_cvt_pk_bf16_f32 v2, v0, s0
	v_lshl_add_u64 v[0:1], v[16:17], 0, v[180:181]
	global_store_short v[0:1], v2, off
	v_mul_f32_e32 v0, v5, v73
	v_cvt_pk_bf16_f32 v2, v0, s0
	v_lshl_add_u64 v[0:1], v[16:17], 0, v[182:183]
	global_store_short v[0:1], v2, off
	v_mul_f32_e32 v0, v6, v74
	v_cvt_pk_bf16_f32 v2, v0, s0
	v_lshl_add_u64 v[0:1], v[16:17], 0, v[184:185]
	global_store_short v[0:1], v2, off
	v_mul_f32_e32 v0, v7, v75
	v_cvt_pk_bf16_f32 v2, v0, s0
	v_lshl_add_u64 v[0:1], v[16:17], 0, v[186:187]
	global_store_short v[0:1], v2, off
	v_mul_f32_e32 v0, v8, v76
	v_cvt_pk_bf16_f32 v2, v0, s0
	v_lshl_add_u64 v[0:1], v[16:17], 0, v[188:189]
	global_store_short v[0:1], v2, off
	v_mul_f32_e32 v0, v9, v77
	v_cvt_pk_bf16_f32 v2, v0, s0
	v_lshl_add_u64 v[0:1], v[16:17], 0, v[190:191]
	global_store_short v[0:1], v2, off
	v_mul_f32_e32 v0, v10, v78
	v_cvt_pk_bf16_f32 v2, v0, s0
	v_lshl_add_u64 v[0:1], v[16:17], 0, v[192:193]
	global_store_short v[0:1], v2, off
	v_mul_f32_e32 v0, v11, v79
	v_cvt_pk_bf16_f32 v2, v0, s0
	v_lshl_add_u64 v[0:1], v[16:17], 0, v[194:195]
	global_store_short v[0:1], v2, off
	v_mul_f32_e32 v0, v12, v64
	v_cvt_pk_bf16_f32 v2, v0, s0
	v_lshl_add_u64 v[0:1], v[16:17], 0, v[196:197]
	global_store_short v[0:1], v2, off
	v_mul_f32_e32 v0, v13, v65
	v_cvt_pk_bf16_f32 v2, v0, s0
	v_lshl_add_u64 v[0:1], v[16:17], 0, v[198:199]
	global_store_short v[0:1], v2, off
	v_mul_f32_e32 v0, v14, v66
	v_cvt_pk_bf16_f32 v2, v0, s0
	v_lshl_add_u64 v[0:1], v[16:17], 0, v[200:201]
	global_store_short v[0:1], v2, off
	v_mul_f32_e32 v0, v15, v67
	s_add_i32 s70, s70, s28
	v_cvt_pk_bf16_f32 v2, v0, s0
	v_lshl_add_u64 v[0:1], v[16:17], 0, v[202:203]
	s_cmpk_gt_i32 s70, 0x23f
	global_store_short v[0:1], v2, off
	s_waitcnt vmcnt(63) expcnt(7) lgkmcnt(15)
	s_barrier
	s_cbranch_scc1 .LBB0_615

; #define LAS __attribute__((address_space(3)))
; #define MFMA32(a, b, c) __builtin_amdgcn_mfma_f32_32x32x16_bf16((a), (b), (c), 0, 0, 0)
; template <int DQK, int DV, int MODE> ...
;     ...
;     for (int t = 0; t < nt; ++t) {
;         const int buf = t & 1;
;         if (t + 1 < nt) FL_LOAD(t + 1);
;         const int kp0 = kstart + 64 * t;
;         const bool band = (MODE == 2) && (t < nband);
;         const bool skip = band && (kp0 > qa + 31 + 128 || kp0 + 63 < qa - 128);
;         if (MODE == 0) {
;             const LAS unsigned char* Kb = lds + buf * BUF; const LAS unsigned char* Vb = Kb + KBYTES;
;             f32x16 p0, p1;
; #pragma unroll
;             for (int e = 0; e < 16; ++e) { p0[e] = 0.f; p1[e] = 0.f; }
; #pragma unroll
;             for (int d0 = 0; d0 < DQK / 16; ++d0) {
;                 const bf16x8 k0 = *(const LAS bf16x8*)(Kb + r * KS + d0 * 32 + h * 16), k1 = *(const LAS bf16x8*)(Kb + (32 + r) * KS + d0 * 32 + h * 16);
;                 p0 = MFMA32(k0, qf[d0], p0); p1 = MFMA32(k1, qf[d0], p1);
;                 if ((d0 & 3) == 3) __builtin_amdgcn_sched_barrier(0);
;             }
;             float mx = fmaxf(fmaxf(p0[0], p0[1]), fmaxf(p1[0], p1[1]));
; #pragma unroll
;             for (int e = 2; e < 16; e += 2) mx = fmaxf(fmaxf(mx, p0[e]), fmaxf(fmaxf(p0[e + 1], p1[e]), p1[e + 1]));
;             mx = fmaxf(mx, __shfl_xor(mx, 32));
;             if (__any(mx > m + 8.f)) {
;                 const float mn = fmaxf(m, mx), al = __builtin_amdgcn_exp2f(m - mn); l *= al; m = mn;
;                 if (h == 0) wsf[r] = al;
;                 f32x4 a4[4];
; #pragma unroll
;                 for (int g = 0; g < 4; ++g) a4[g] = *(const LAS f32x4*)(wsf + 8 * g + 4 * h);
; #pragma unroll
;                 for (int d = 0; d < DV / 32; ++d)
; #pragma unroll
;                     for (int e = 0; e < 16; ++e) o[d][e] *= a4[e >> 2][e & 3];
;             }
.LBB0_597:
	s_and_b32 s72, s59, 1
	s_add_i32 s59, s59, 1
	s_cmp_lt_u32 s59, s9
	s_cselect_b64 s[6:7], -1, 0
	s_and_b64 s[6:7], s[6:7], exec
	s_cselect_b32 s6, 0, s9
	s_cselect_b32 s7, s41, s39
	s_cselect_b32 s34, s40, s38
	s_lshl_b32 s6, s6, 6
	s_sub_i32 s6, s71, s6
	s_add_u32 s6, s34, s6
	s_addc_u32 s7, s7, 0
	s_lshl_b64 s[44:45], s[6:7], 12
	s_add_u32 s44, s55, s44
	s_mul_i32 s34, s72, 0xb400
	s_addc_u32 s45, s58, s45
	s_add_i32 s73, s34, 0
	v_add3_u32 v222, s73, v213, v214
	ds_read_b128 v[224:227], v222
	ds_read_b128 v[228:231], v222 offset:12800
	ds_read_b128 v[232:235], v222 offset:32
	ds_read_b128 v[176:179], v222 offset:12832
	ds_read_b128 v[180:183], v222 offset:64
	ds_read_b128 v[184:187], v222 offset:12864
	ds_read_b128 v[188:191], v222 offset:96
	ds_read_b128 v[192:195], v222 offset:12896
	ds_read_b128 v[196:199], v222 offset:128
	ds_read_b128 v[200:203], v222 offset:12928
	v_lshl_add_u64 v[112:113], s[44:45], 0, v[170:171]
	s_mul_i32 s34, s7, 0x1a00
	v_add_co_u32_e32 v114, vcc, s69, v112
	v_lshl_add_u64 v[174:175], v[112:113], 0, s[4:5]
	s_nop 0
	v_addc_co_u32_e32 v115, vcc, 0, v113, vcc
	v_mad_u64_u32 v[96:97], s[6:7], s6, v218, v[204:205]
	v_add_u32_e32 v97, s34, v97
	global_load_dwordx4 v[96:99], v[96:97], off offset:2048
	s_nop 0
	global_load_dwordx4 v[104:107], v[112:113], off
	global_load_dwordx4 v[100:103], v[112:113], off offset:256
	global_load_dwordx4 v[112:115], v[114:115], off
	s_nop 0
	global_load_dwordx4 v[108:111], v[174:175], off offset:256
	s_waitcnt lgkmcnt(9)
	v_mfma_f32_32x32x16_bf16 v[64:79], v[224:227], v[160:163], 0
	ds_read_b128 v[224:227], v222 offset:160
	s_waitcnt lgkmcnt(9)
	v_mfma_f32_32x32x16_bf16 v[80:95], v[228:231], v[160:163], 0
	ds_read_b128 v[228:231], v222 offset:12960
	s_waitcnt lgkmcnt(9)
	v_mfma_f32_32x32x16_bf16 v[64:79], v[232:235], v[156:159], v[64:79]
	ds_read_b128 v[232:235], v222 offset:192
	s_waitcnt lgkmcnt(9)
	v_mfma_f32_32x32x16_bf16 v[80:95], v[176:179], v[156:159], v[80:95]
	ds_read_b128 v[176:179], v222 offset:12992
	s_waitcnt lgkmcnt(9)
	v_mfma_f32_32x32x16_bf16 v[64:79], v[180:183], v[152:155], v[64:79]
	ds_read_b128 v[180:183], v222 offset:224
	s_waitcnt lgkmcnt(9)
	v_mfma_f32_32x32x16_bf16 v[80:95], v[184:187], v[152:155], v[80:95]
	ds_read_b128 v[184:187], v222 offset:13024
	s_waitcnt lgkmcnt(9)
	v_mfma_f32_32x32x16_bf16 v[64:79], v[188:191], v[148:151], v[64:79]
	ds_read_b128 v[188:191], v222 offset:256
	s_waitcnt lgkmcnt(9)
	v_mfma_f32_32x32x16_bf16 v[80:95], v[192:195], v[148:151], v[80:95]
	ds_read_b128 v[192:195], v222 offset:13056
	s_waitcnt lgkmcnt(9)
	v_mfma_f32_32x32x16_bf16 v[64:79], v[196:199], v[140:143], v[64:79]
	ds_read_b128 v[196:199], v222 offset:288
	s_waitcnt lgkmcnt(9)
	v_mfma_f32_32x32x16_bf16 v[80:95], v[200:203], v[140:143], v[80:95]
	ds_read_b128 v[200:203], v222 offset:13088
	s_waitcnt lgkmcnt(9)
	v_mfma_f32_32x32x16_bf16 v[64:79], v[224:227], v[132:135], v[64:79]
	ds_read_b128 v[224:227], v222 offset:320
	s_waitcnt lgkmcnt(9)
	v_mfma_f32_32x32x16_bf16 v[80:95], v[228:231], v[132:135], v[80:95]
	ds_read_b128 v[228:231], v222 offset:13120
	s_waitcnt lgkmcnt(9)
	v_mfma_f32_32x32x16_bf16 v[64:79], v[232:235], v[124:127], v[64:79]
	ds_read_b128 v[232:235], v222 offset:352
	s_waitcnt lgkmcnt(9)
	v_mfma_f32_32x32x16_bf16 v[80:95], v[176:179], v[124:127], v[80:95]
	ds_read_b128 v[176:179], v222 offset:13152
	s_waitcnt lgkmcnt(9)
	v_mfma_f32_32x32x16_bf16 v[64:79], v[180:183], v[116:119], v[64:79]
	s_waitcnt lgkmcnt(8)
	v_mfma_f32_32x32x16_bf16 v[80:95], v[184:187], v[116:119], v[80:95]
	s_waitcnt lgkmcnt(7)
	v_mfma_f32_32x32x16_bf16 v[64:79], v[188:191], v[144:147], v[64:79]
	s_waitcnt lgkmcnt(6)
	v_mfma_f32_32x32x16_bf16 v[80:95], v[192:195], v[144:147], v[80:95]
	s_waitcnt lgkmcnt(5)
	v_mfma_f32_32x32x16_bf16 v[64:79], v[196:199], v[136:139], v[64:79]
	s_waitcnt lgkmcnt(4)
	v_mfma_f32_32x32x16_bf16 v[80:95], v[200:203], v[136:139], v[80:95]
	s_waitcnt lgkmcnt(3)
	v_mfma_f32_32x32x16_bf16 v[64:79], v[224:227], v[128:131], v[64:79]
	s_waitcnt lgkmcnt(2)
	v_mfma_f32_32x32x16_bf16 v[80:95], v[228:231], v[128:131], v[80:95]
	s_waitcnt lgkmcnt(1)
	v_mfma_f32_32x32x16_bf16 v[64:79], v[232:235], v[120:123], v[64:79]
	s_waitcnt lgkmcnt(0)
	v_mfma_f32_32x32x16_bf16 v[80:95], v[176:179], v[120:123], v[80:95]
	s_nop 11
	v_max_f32_e32 v222, v81, v81
	v_max_f32_e32 v224, v80, v80
	v_max_f32_e32 v222, v224, v222
	v_max3_f32 v222, v64, v65, v222
	v_max3_f32 v224, v67, v82, v83
	v_max3_f32 v222, v222, v66, v224
	v_max3_f32 v224, v69, v84, v85
	v_max3_f32 v222, v222, v68, v224
	v_max3_f32 v224, v71, v86, v87
	v_max3_f32 v222, v222, v70, v224
	v_max3_f32 v224, v73, v88, v89
	v_max3_f32 v222, v222, v72, v224
	v_max3_f32 v224, v75, v90, v91
	v_max3_f32 v222, v222, v74, v224
	v_max3_f32 v224, v77, v92, v93
	v_max3_f32 v222, v222, v76, v224
	v_max3_f32 v224, v79, v94, v95
	v_max3_f32 v222, v222, v78, v224
	ds_bpermute_b32 v224, v215, v222
	s_waitcnt lgkmcnt(0)
	v_max_f32_e32 v224, v224, v224
	v_max_f32_e32 v222, v222, v224
	v_add_f32_e32 v224, 0x41000000, v223
	v_cmp_gt_f32_e32 vcc, v222, v224
	s_cbranch_vccz .LBB0_601
	v_max_f32_e32 v222, v222, v222
	v_max_f32_e32 v224, v223, v223
	v_max_f32_e32 v222, v224, v222
	v_sub_f32_e32 v223, v223, v222
	v_exp_f32_e32 v223, v223
	s_and_saveexec_b64 s[44:45], s[2:3]
	ds_write_b32 v220, v223
	s_or_b64 exec, exec, s[44:45]
	ds_read_b128 v[224:227], v219 offset:96
	ds_read_b128 v[228:231], v219 offset:64
	ds_read_b128 v[232:235], v219 offset:32
	ds_read_b128 v[236:239], v219
	v_mul_f32_e32 v221, v221, v223
	s_waitcnt lgkmcnt(3)
	v_pk_mul_f32 v[62:63], v[62:63], v[226:227]
	s_waitcnt lgkmcnt(2)
	v_pk_mul_f32 v[58:59], v[58:59], v[230:231]
	s_waitcnt lgkmcnt(1)
	v_pk_mul_f32 v[54:55], v[54:55], v[234:235]
	s_waitcnt lgkmcnt(0)
	v_pk_mul_f32 v[50:51], v[50:51], v[238:239]
	v_pk_mul_f32 v[60:61], v[60:61], v[224:225]
	v_pk_mul_f32 v[56:57], v[56:57], v[228:229]
	v_pk_mul_f32 v[52:53], v[52:53], v[232:233]
	v_pk_mul_f32 v[48:49], v[48:49], v[236:237]
	v_pk_mul_f32 v[46:47], v[46:47], v[226:227]
	v_pk_mul_f32 v[42:43], v[42:43], v[230:231]
	v_pk_mul_f32 v[38:39], v[38:39], v[234:235]
	v_pk_mul_f32 v[34:35], v[34:35], v[238:239]
	v_pk_mul_f32 v[44:45], v[44:45], v[224:225]
	v_pk_mul_f32 v[40:41], v[40:41], v[228:229]
	v_pk_mul_f32 v[36:37], v[36:37], v[232:233]
	v_pk_mul_f32 v[32:33], v[32:33], v[236:237]
	v_pk_mul_f32 v[30:31], v[30:31], v[226:227]
	v_pk_mul_f32 v[26:27], v[26:27], v[230:231]
	v_pk_mul_f32 v[22:23], v[22:23], v[234:235]
	v_pk_mul_f32 v[18:19], v[18:19], v[238:239]
	v_pk_mul_f32 v[28:29], v[28:29], v[224:225]
	v_pk_mul_f32 v[24:25], v[24:25], v[228:229]
	v_pk_mul_f32 v[20:21], v[20:21], v[232:233]
	v_pk_mul_f32 v[16:17], v[16:17], v[236:237]
	v_pk_mul_f32 v[14:15], v[14:15], v[226:227]
	v_pk_mul_f32 v[10:11], v[10:11], v[230:231]
	v_pk_mul_f32 v[6:7], v[6:7], v[234:235]
	v_pk_mul_f32 v[2:3], v[2:3], v[238:239]
	v_pk_mul_f32 v[12:13], v[12:13], v[224:225]
	v_pk_mul_f32 v[8:9], v[8:9], v[228:229]
	v_pk_mul_f32 v[4:5], v[4:5], v[232:233]
	v_pk_mul_f32 v[0:1], v[0:1], v[236:237]
	s_branch .LBB0_602

; #define LAS __attribute__((address_space(3)))
; __device__ __forceinline__ unsigned pk_bf16(float lo, float hi) { f32x2 v = {lo, hi}; bf16x2_t b = __builtin_convertvector(v, bf16x2_t); return __builtin_bit_cast(unsigned, b); }
; #define MFMA32(a, b, c) __builtin_amdgcn_mfma_f32_32x32x16_bf16((a), (b), (c), 0, 0, 0)
; template <int DQK, int DV, int MODE> ...
;     ...
;             float ls = 0.f;
; #pragma unroll
;             for (int e = 0; e < 16; ++e) { p0[e] = __builtin_amdgcn_exp2f(p0[e] - m); p1[e] = __builtin_amdgcn_exp2f(p1[e] - m); ls += p0[e] + p1[e]; }
;             l += ls;
;             bf16x8 pa[4];
; #pragma unroll
;             for (int ks = 0; ks < 4; ++ks) { u32x4 w;
; #pragma unroll
;                 for (int j = 0; j < 4; ++j) { const int e = 8 * (ks & 1) + 2 * j; w[j] = (ks < 2) ? pk_bf16(p0[e], p0[e + 1]) : pk_bf16(p1[e], p1[e + 1]); }
;                 pa[ks] = __builtin_bit_cast(bf16x8, w); }
; #pragma unroll
;             for (int ks = 0; ks < 4; ++ks) {
; #pragma unroll
;                 for (int d = 0; d < DV / 32; ++d) {
;                     const LAS unsigned char* vp = Vb + vlane + (16 * ks) * VS + d * 64;
;                     const s16x4 lo = tr_read(vp), hi = tr_read(vp + 8 * VS);
;                     o[d] = MFMA32(pa[ks], __builtin_shufflevector(lo, hi, 0, 1, 2, 3, 4, 5, 6, 7), o[d]);
.LBB0_602:
	v_add3_u32 v173, s73, v210, v207
	ds_read_b64_tr_b16 v[176:177], v173 offset:25600
	ds_read_b64_tr_b16 v[178:179], v173 offset:28160
	ds_read_b64_tr_b16 v[180:181], v173 offset:25664
	ds_read_b64_tr_b16 v[182:183], v173 offset:28224
	ds_read_b64_tr_b16 v[184:185], v173 offset:25728
	ds_read_b64_tr_b16 v[186:187], v173 offset:28288
	ds_read_b64_tr_b16 v[188:189], v173 offset:25792
	ds_read_b64_tr_b16 v[190:191], v173 offset:28352
	v_sub_f32_e32 v64, v64, v222
	v_exp_f32_e32 v223, v64
	v_sub_f32_e32 v64, v80, v222
	v_exp_f32_e32 v232, v64
	v_sub_f32_e32 v64, v65, v222
	v_sub_f32_e32 v66, v66, v222
	v_exp_f32_e32 v80, v64
	v_sub_f32_e32 v64, v81, v222
	v_exp_f32_e32 v81, v66
	v_sub_f32_e32 v66, v82, v222
	v_exp_f32_e32 v233, v64
	v_exp_f32_e32 v234, v66
	v_sub_f32_e32 v66, v67, v222
	v_exp_f32_e32 v82, v66
	v_sub_f32_e32 v66, v83, v222
	v_exp_f32_e32 v235, v66
	v_add_f32_e32 v64, v223, v232
	v_add_f32_e32 v64, 0, v64
	v_add_f32_e32 v65, v80, v233
	v_add_f32_e32 v64, v65, v64
	v_add_f32_e32 v65, v81, v234
	v_add_f32_e32 v64, v65, v64
	v_add_f32_e32 v65, v82, v235
	v_add_f32_e32 v83, v65, v64
	v_sub_f32_e32 v64, v68, v222
	v_exp_f32_e32 v67, v64
	v_sub_f32_e32 v64, v84, v222
	v_exp_f32_e32 v225, v64
	v_sub_f32_e32 v64, v69, v222
	v_exp_f32_e32 v66, v64
	v_sub_f32_e32 v64, v85, v222
	v_exp_f32_e32 v224, v64
	v_sub_f32_e32 v64, v70, v222
	v_exp_f32_e32 v69, v64
	v_sub_f32_e32 v64, v86, v222
	v_exp_f32_e32 v85, v64
	v_sub_f32_e32 v64, v71, v222
	v_exp_f32_e32 v68, v64
	v_sub_f32_e32 v64, v87, v222
	v_exp_f32_e32 v84, v64
	v_pk_add_f32 v[64:65], v[66:67], v[224:225]
	v_pk_mov_b32 v[66:67], v[66:67], v[66:67] op_sel:[1,0]
	v_add_f32_e32 v65, v65, v83
	v_add_f32_e32 v70, v64, v65
	v_pk_add_f32 v[64:65], v[68:69], v[84:85]
	v_pk_mov_b32 v[68:69], v[68:69], v[68:69] op_sel:[1,0]
	v_add_f32_e32 v65, v65, v70
	v_add_f32_e32 v83, v64, v65
	v_sub_f32_e32 v64, v72, v222
	v_exp_f32_e32 v71, v64
	v_sub_f32_e32 v64, v88, v222
	v_exp_f32_e32 v87, v64
	v_sub_f32_e32 v64, v73, v222
	v_exp_f32_e32 v70, v64
	v_sub_f32_e32 v64, v89, v222
	v_exp_f32_e32 v86, v64
	v_sub_f32_e32 v64, v74, v222
	v_exp_f32_e32 v89, v64
	v_sub_f32_e32 v64, v90, v222
	v_exp_f32_e32 v227, v64
	v_sub_f32_e32 v64, v75, v222
	v_exp_f32_e32 v88, v64
	v_sub_f32_e32 v64, v91, v222
	v_exp_f32_e32 v226, v64
	v_pk_add_f32 v[64:65], v[70:71], v[86:87]
	v_cvt_pk_bf16_f32 v66, v66, v67
	v_add_f32_e32 v65, v65, v83
	v_add_f32_e32 v72, v64, v65
	v_pk_add_f32 v[64:65], v[88:89], v[226:227]
	v_cvt_pk_bf16_f32 v67, v68, v69
	v_add_f32_e32 v65, v65, v72
	v_add_f32_e32 v72, v64, v65
	v_sub_f32_e32 v64, v76, v222
	v_exp_f32_e32 v91, v64
	v_sub_f32_e32 v64, v92, v222
	v_exp_f32_e32 v229, v64
	v_sub_f32_e32 v64, v77, v222
	v_exp_f32_e32 v90, v64
	v_sub_f32_e32 v64, v93, v222
	v_exp_f32_e32 v228, v64
	v_sub_f32_e32 v64, v78, v222
	v_exp_f32_e32 v93, v64
	v_sub_f32_e32 v64, v94, v222
	v_exp_f32_e32 v231, v64
	v_sub_f32_e32 v64, v79, v222
	v_exp_f32_e32 v92, v64
	v_sub_f32_e32 v64, v95, v222
	v_exp_f32_e32 v230, v64
	v_pk_add_f32 v[64:65], v[90:91], v[228:229]
	v_pk_mov_b32 v[94:95], v[70:71], v[70:71] op_sel:[1,0]
	v_add_f32_e32 v65, v65, v72
	v_add_f32_e32 v72, v64, v65
	v_pk_add_f32 v[64:65], v[92:93], v[230:231]
	v_pk_mov_b32 v[84:85], v[84:85], v[84:85] op_sel:[1,0]
	v_add_f32_e32 v65, v65, v72
	v_add_f32_e32 v236, v64, v65
	v_cvt_pk_bf16_f32 v64, v223, v80
	v_cvt_pk_bf16_f32 v65, v81, v82
	s_waitcnt lgkmcnt(4)
	ds_read_b64_tr_b16 v[192:193], v173 offset:30720
	ds_read_b64_tr_b16 v[194:195], v173 offset:33280
	ds_read_b64_tr_b16 v[196:197], v173 offset:30784
	ds_read_b64_tr_b16 v[198:199], v173 offset:33344
	ds_read_b64_tr_b16 v[200:201], v173 offset:30848
	ds_read_b64_tr_b16 v[202:203], v173 offset:33408
	ds_read_b64_tr_b16 v[80:81], v173 offset:30912
	ds_read_b64_tr_b16 v[82:83], v173 offset:33472
	s_waitcnt lgkmcnt(8)
; #define LAS __attribute__((address_space(3)))
; #define MFMA32(a, b, c) __builtin_amdgcn_mfma_f32_32x32x16_bf16((a), (b), (c), 0, 0, 0)
; template <int DQK, int DV, int MODE> ...
;     ...
;             for (int ks = 0; ks < 4; ++ks) {
; #pragma unroll
;                 for (int d = 0; d < DV / 32; ++d) {
;                     const LAS unsigned char* vp = Vb + vlane + (16 * ks) * VS + d * 64;
;                     const s16x4 lo = tr_read(vp), hi = tr_read(vp + 8 * VS);
;                     o[d] = MFMA32(pa[ks], __builtin_shufflevector(lo, hi, 0, 1, 2, 3, 4, 5, 6, 7), o[d]);
;                 }
;                 __builtin_amdgcn_sched_barrier(0);
;             }
;     ...
;         if (t + 1 < nt) FL_STORE(buf ^ 1);
;         __syncthreads();
	v_mfma_f32_32x32x16_bf16 v[48:63], v[64:67], v[176:179], v[48:63]
	v_pk_mov_b32 v[70:71], v[88:89], v[88:89] op_sel:[1,0]
	v_pk_mov_b32 v[88:89], v[92:93], v[92:93] op_sel:[1,0]
	v_cvt_pk_bf16_f32 v69, v70, v71
	v_pk_mov_b32 v[70:71], v[90:91], v[90:91] op_sel:[1,0]
	v_cvt_pk_bf16_f32 v68, v94, v95
	v_cvt_pk_bf16_f32 v70, v70, v71
	v_cvt_pk_bf16_f32 v71, v88, v89
	v_mfma_f32_32x32x16_bf16 v[32:47], v[64:67], v[180:183], v[32:47]
	v_pk_mov_b32 v[74:75], v[224:225], v[224:225] op_sel:[1,0]
	v_cvt_pk_bf16_f32 v72, v232, v233
	v_cvt_pk_bf16_f32 v74, v74, v75
	v_cvt_pk_bf16_f32 v75, v84, v85
	v_pk_mov_b32 v[84:85], v[86:87], v[86:87] op_sel:[1,0]
	v_cvt_pk_bf16_f32 v73, v234, v235
	v_mfma_f32_32x32x16_bf16 v[16:31], v[64:67], v[184:187], v[16:31]
	v_pk_mov_b32 v[78:79], v[226:227], v[226:227] op_sel:[1,0]
	v_cvt_pk_bf16_f32 v76, v84, v85
	v_cvt_pk_bf16_f32 v77, v78, v79
	v_pk_mov_b32 v[78:79], v[228:229], v[228:229] op_sel:[1,0]
	v_pk_mov_b32 v[84:85], v[230:231], v[230:231] op_sel:[1,0]
	v_cvt_pk_bf16_f32 v78, v78, v79
	v_cvt_pk_bf16_f32 v79, v84, v85
	v_mfma_f32_32x32x16_bf16 v[0:15], v[64:67], v[188:191], v[0:15]
	s_waitcnt lgkmcnt(4)
	ds_read_b64_tr_b16 v[176:177], v173 offset:35840
	ds_read_b64_tr_b16 v[178:179], v173 offset:38400
	ds_read_b64_tr_b16 v[180:181], v173 offset:35904
	ds_read_b64_tr_b16 v[182:183], v173 offset:38464
	ds_read_b64_tr_b16 v[184:185], v173 offset:35968
	ds_read_b64_tr_b16 v[186:187], v173 offset:38528
	ds_read_b64_tr_b16 v[188:189], v173 offset:36032
	ds_read_b64_tr_b16 v[190:191], v173 offset:38592
	s_waitcnt lgkmcnt(8)
	v_mfma_f32_32x32x16_bf16 v[48:63], v[68:71], v[192:195], v[48:63]
	v_mfma_f32_32x32x16_bf16 v[32:47], v[68:71], v[196:199], v[32:47]
	v_mfma_f32_32x32x16_bf16 v[16:31], v[68:71], v[200:203], v[16:31]
	v_mfma_f32_32x32x16_bf16 v[0:15], v[68:71], v[80:83], v[0:15]
	s_waitcnt lgkmcnt(4)
	ds_read_b64_tr_b16 v[192:193], v173 offset:40960
	ds_read_b64_tr_b16 v[194:195], v173 offset:43520
	ds_read_b64_tr_b16 v[196:197], v173 offset:41024
	ds_read_b64_tr_b16 v[198:199], v173 offset:43584
	ds_read_b64_tr_b16 v[200:201], v173 offset:41088
	ds_read_b64_tr_b16 v[202:203], v173 offset:43648
	ds_read_b64_tr_b16 v[80:81], v173 offset:41152
	ds_read_b64_tr_b16 v[82:83], v173 offset:43712
	s_waitcnt lgkmcnt(8)
	v_mfma_f32_32x32x16_bf16 v[48:63], v[72:75], v[176:179], v[48:63]
	v_mfma_f32_32x32x16_bf16 v[32:47], v[72:75], v[180:183], v[32:47]
	v_mfma_f32_32x32x16_bf16 v[16:31], v[72:75], v[184:187], v[16:31]
	v_mfma_f32_32x32x16_bf16 v[0:15], v[72:75], v[188:191], v[0:15]
	s_waitcnt lgkmcnt(0)
	v_mfma_f32_32x32x16_bf16 v[48:63], v[76:79], v[192:195], v[48:63]
	v_mfma_f32_32x32x16_bf16 v[32:47], v[76:79], v[196:199], v[32:47]
	v_mfma_f32_32x32x16_bf16 v[16:31], v[76:79], v[200:203], v[16:31]
	v_mfma_f32_32x32x16_bf16 v[0:15], v[76:79], v[80:83], v[0:15]
	s_xor_b32 s6, s72, 1
	s_mul_i32 s6, s6, 0xb400
	s_add_i32 s6, s6, 0
	v_add_u32_e32 v64, s6, v208
	s_waitcnt vmcnt(3)
	ds_write_b128 v64, v[104:107]
	s_waitcnt vmcnt(1)
	ds_write_b128 v64, v[112:115] offset:12800
	v_add_u32_e32 v64, s6, v212
	s_add_i32 s71, s71, 64
	v_add_f32_e32 v221, v221, v236
	ds_write_b128 v64, v[96:99] offset:256
	v_add_u32_e32 v64, s6, v216
	s_cmp_eq_u32 s54, s59
	ds_write_b128 v64, v[100:103] offset:25600
	s_waitcnt vmcnt(0)
	ds_write_b128 v64, v[108:111] offset:35840
	s_waitcnt lgkmcnt(0)
	s_barrier
	s_cbranch_scc1 .LBB0_604
	v_mov_b32_e32 v223, v222
	s_branch .LBB0_597

; #define LAS __attribute__((address_space(3)))
; template <int DQK, int DV, int MODE> ...
;     ...
;     constexpr int QS = (MODE == 2) ? NIN1 : NQ;
;     const int tid = threadIdx.x, lane = tid & 63, r = lane & 31, h = lane >> 5, wid = __builtin_amdgcn_readfirstlane(tid >> 6);
;     LAS float* wsf = (LAS float*)(lds + 2 * BUF) + wid * 32;
;     const int q0 = qblk * 256;
;     const long qrow_base = ctxq ? (long)MLAT + b * CTXL : (long)b * SEQ + q0;
;     const int qcol0 = (MODE == 2) ? hd * 64 : hd * 192;
;     int kstart = 0, nband = 0, nt;
;     if (MODE == 0) { nband = ctxq ? 0 : 32; nt = nband + 4; }
;     else { kstart = q0 - 128 < 0 ? 0 : q0 - 128; const int kend = q0 + 384 > SEQ ? SEQ : q0 + 384; nband = (kend - kstart) >> 6; nt = nband + 4; }
;     const long ctx_base = (long)MLAT + b * CTXL;
;     ...
;     bf16x8 qf[DQK / 16];
;     { const bf16_t* qp = Qb + (size_t)(qrow_base + wid * 32 + r) * QS + qcol0 + h * 8;
; #pragma unroll
;       for (int d0 = 0; d0 < DQK / 16; ++d0) qf[d0] = *(const bf16x8*)(qp + d0 * 16); }
; __global__ void __launch_bounds__(512, 2) mk_fwd(Args args) {
;     ...
;         for (int j = F.vcu; j < 2048; j += F.G) { const int hd = ((j >> 6) & 3) * 8 + (j & 7);
;             flash_unit<64, 64, 2>(F.lds, QKV1, QKV1, nullptr, MIXb, j >> 8, hd, ((j >> 3) + (j >> 8)) & 7, args.in[19][hd] * 1.4426950408889634f, false); }
.LBB0_1369:
	v_readfirstlane_b32 s52, v165
	s_lshr_b32 s9, s40, 3
	s_and_b32 s27, s9, 24
	s_ashr_i32 s4, s40, 8
	s_lshr_b32 s5, s52, 6
	s_or_b32 s41, s27, s5
	s_lshl_b32 s5, s41, 2
	v_mov_b32_e32 v0, s5
	s_lshr_b32 s5, s52, 1
	s_and_b32 s26, s5, 0x7fffffe0
	s_and_b32 s5, s40, 63
	s_lshl_b32 s36, s5, 5
	s_ashr_i32 s5, s4, 31
	s_lshl_b64 s[22:23], s[4:5], 11
	s_sub_i32 s37, s36, 0x80
	s_max_i32 s37, s37, 0
	s_and_b32 s37, s37, 0xffffffc0
	s_add_i32 s5, s36, 0xdf
	s_and_b32 s5, s5, 0xffffffc0
	s_min_u32 s5, s5, 0x800
	s_sub_i32 s53, s5, s37
	s_and_b32 s6, s40, 0xffffff00
	s_or_b32 s4, s22, s36
	s_ashr_i32 s44, s53, 6
	s_ashr_i32 s7, s6, 31
	s_add_u32 s16, s4, 0
	v_or_b32_e32 v1, s16, v72
	s_addc_u32 s17, s23, 0
	v_mad_u64_u32 v[2:3], s[4:5], v1, s38, v[112:113]
	v_mad_i32_i24 v3, s17, v124, v3
	s_lshl_b32 s12, s41, 7
	v_lshl_add_u64 v[2:3], v[2:3], 0, s[12:13]
	v_lshl_add_u64 v[2:3], v[2:3], 0, v[110:111]
	global_load_dword v0, v0, s[42:43]
	s_nop 0
	global_load_dwordx4 v[48:51], v[2:3], off
	global_load_dwordx4 v[52:55], v[2:3], off offset:32
	global_load_dwordx4 v[56:59], v[2:3], off offset:64
	global_load_dwordx4 v[60:63], v[2:3], off offset:96
	s_add_u32 s12, s6, 0x4000
	s_addc_u32 s45, s7, 0
	s_cmp_lt_i32 s44, 1
	s_mov_b64 s[24:25], -1
	s_cbranch_scc0 .LBB0_1371
	s_sub_i32 s4, 0, s53
	s_add_u32 s4, s12, s4
	s_addc_u32 s5, s45, 0
	s_mov_b64 s[24:25], 0

; template <int DQK, int DV, int MODE> ...
;     ...
;     const int qa = q0 + wid * 32;
;     const int vlane = (4 * h + ((lane & 15) >> 2)) * VS + (16 * ((lane >> 4) & 1) + 4 * (lane & 3)) * 2;
;     FL_LOAD(0); FL_STORE(0); __syncthreads();
;     if (wid >= 4) __builtin_amdgcn_s_setprio(1);
.LBB0_1373:
	s_mulk_i32 s5, 0x1400
	s_mul_hi_u32 s6, s4, 0x1400
	s_add_i32 s6, s6, s5
	s_mulk_i32 s4, 0x1400
	s_add_u32 s4, s20, s4
	s_addc_u32 s5, s21, s6
	s_lshl_b32 s6, s27, 4
	s_add_u32 s4, s4, s6
	s_addc_u32 s5, s5, 0
	v_lshl_add_u64 v[2:3], s[4:5], 0, v[76:77]
	v_lshl_add_u64 v[4:5], v[2:3], 0, s[14:15]
	v_add_co_u32_e32 v2, vcc, 0x1000, v2
	s_cmpk_lt_u32 s52, 0x100
	s_nop 0
	v_addc_co_u32_e32 v3, vcc, 0, v3, vcc
	global_load_dwordx4 v[64:67], v[2:3], off
	global_load_dwordx4 v[68:71], v[4:5], off offset:512
	v_add_co_u32_e32 v2, vcc, 0x50000, v2
	s_nop 1
	v_addc_co_u32_e32 v3, vcc, 0, v3, vcc
	v_add_co_u32_e32 v4, vcc, 0x50000, v4
	s_nop 1
	v_addc_co_u32_e32 v5, vcc, 0, v5, vcc
	global_load_dwordx4 v[152:155], v[2:3], off
	global_load_dwordx4 v[156:159], v[4:5], off offset:512
	s_waitcnt vmcnt(2)
	ds_write_b128 v117, v[64:67]
	ds_write_b128 v122, v[68:71] offset:9216
	s_waitcnt lgkmcnt(0)
	s_barrier
	s_cbranch_scc1 .LBB0_1375
	s_setprio 1
.LBB0_1375:
	s_lshl_b32 s4, s26, 2
	s_add_i32 s4, s4, 0
	s_cmp_lt_i32 s44, -3
	v_lshl_add_u32 v127, v72, 2, s4
	v_lshl_add_u32 v126, v114, 2, s4
	s_cbranch_scc1 .LBB0_1410
	s_mov_b32 s5, s36
	s_sub_i32 s6, s36, s37
	v_mul_f32_e32 v131, 0x3fb8aa3b, v0
	v_or_b32_e32 v0, s6, v72
	s_lshl_b32 s4, s27, 3
	s_mov_b32 s56, s36
	v_sub_u32_e32 v0, v114, v0
	s_add_i32 s52, s44, 4
	s_or_b32 s22, s22, s37
	s_add_i32 s53, s56, 0x9f
	s_add_i32 s54, s56, 0xffffff80
	s_add_i32 s55, s56, 0xffffff9f
	s_addk_i32 s56, 0x61
	s_sub_i32 s57, s5, s6
	v_mov_b32_e32 v128, v0
	v_mov_b32_e32 v16, v75
	v_mov_b32_e32 v17, v75
	v_mov_b32_e32 v18, v75
	v_mov_b32_e32 v19, v75
	v_mov_b32_e32 v20, v75
	v_mov_b32_e32 v21, v75
	v_mov_b32_e32 v22, v75
	v_mov_b32_e32 v23, v75
	v_mov_b32_e32 v24, v75
	v_mov_b32_e32 v25, v75
	v_mov_b32_e32 v26, v75
	v_mov_b32_e32 v27, v75
	v_mov_b32_e32 v28, v75
	v_mov_b32_e32 v29, v75
	v_mov_b32_e32 v30, v75
	v_mov_b32_e32 v31, v75
	v_mov_b32_e32 v0, v75
	v_mov_b32_e32 v1, v75
	v_mov_b32_e32 v2, v75
	v_mov_b32_e32 v3, v75
	v_mov_b32_e32 v4, v75
	v_mov_b32_e32 v5, v75
	v_mov_b32_e32 v6, v75
	v_mov_b32_e32 v7, v75
	v_mov_b32_e32 v8, v75
	v_mov_b32_e32 v9, v75
	v_mov_b32_e32 v10, v75
	v_mov_b32_e32 v11, v75
	v_mov_b32_e32 v12, v75
	v_mov_b32_e32 v13, v75
	v_mov_b32_e32 v14, v75
	v_mov_b32_e32 v15, v75
	v_mov_b32_e32 v129, 0.5
	s_mov_b32 s58, -4
	s_mov_b32 s59, 64
	s_lshl_b32 s60, s4, 1
	s_branch .LBB0_1378

; template <int DQK, int DV, int MODE> ...
;     ...
;     for (int t = 0; t < nt; ++t) {
;         const int buf = t & 1;
;         if (t + 1 < nt) FL_LOAD(t + 1);
.LBB0_1378:
	s_add_i32 s4, s58, 5
	s_cmp_lt_i32 s4, s52
	s_cselect_b64 s[24:25], -1, 0
	s_add_i32 s4, s58, 6
	s_cmp_ge_i32 s4, s52
	s_cbranch_scc1 .LBB0_1380
	s_cmp_lt_i32 s4, s44
	s_cselect_b64 s[4:5], -1, 0
	s_and_b64 s[4:5], s[4:5], exec
	s_cselect_b32 s4, 0, s44
	s_cselect_b32 s5, s23, s45
	s_cselect_b32 s6, s22, s12
	s_lshl_b32 s4, s4, 6
	s_sub_i32 s4, s59, s4
	s_add_i32 s4, s4, 64
	s_add_u32 s4, s6, s4
	s_addc_u32 s5, s5, 0
	s_mulk_i32 s5, 0x1400
	s_mul_hi_u32 s6, s4, 0x1400
	s_add_i32 s6, s6, s5
	s_mulk_i32 s4, 0x1400
	s_add_u32 s4, s20, s4
	s_addc_u32 s5, s21, s6
	s_add_u32 s4, s4, s60
	s_addc_u32 s5, s5, 0
	v_lshl_add_u64 v[32:33], s[4:5], 0, v[76:77]
	v_lshl_add_u64 v[34:35], v[32:33], 0, s[14:15]
	v_add_co_u32_e32 v32, vcc, 0x1000, v32
	s_nop 1
	v_addc_co_u32_e32 v33, vcc, 0, v33, vcc
	s_bitcmp1_b32 s58, 0
	s_cbranch_scc1 .Lswa_pf_odd
	global_load_dwordx4 v[64:67], v[32:33], off
	global_load_dwordx4 v[68:71], v[34:35], off offset:512
	s_branch .LBB0_1380
.Lswa_pf_odd:
	global_load_dwordx4 v[152:155], v[32:33], off
	global_load_dwordx4 v[156:159], v[34:35], off offset:512

; template <int DQK, int DV, int MODE> ...
;     ...
;         if (t + 1 < nt) FL_STORE(buf ^ 1);
;         __syncthreads();
.LBB0_1383:
	s_xor_b32 s4, s61, 1
	s_mulk_i32 s4, 0x5400
	s_add_i32 s4, s4, 0
	v_add_u32_e32 v32, s4, v73
	v_add_u32_e32 v33, s4, v121
	s_add_i32 s4, s58, 6
	s_cmp_ge_i32 s4, s52
	s_cbranch_scc1 .Lswa_w_last
	s_bitcmp1_b32 s58, 0
	s_cbranch_scc1 .Lswa_w_odd
	s_waitcnt vmcnt(3)
	ds_write_b128 v32, v[152:155]
	s_waitcnt vmcnt(2)
	ds_write_b128 v33, v[156:159] offset:9216
	s_branch .LBB0_1377
.Lswa_w_odd:
	s_waitcnt vmcnt(3)
	ds_write_b128 v32, v[64:67]
	s_waitcnt vmcnt(2)
	ds_write_b128 v33, v[68:71] offset:9216
	s_branch .LBB0_1377
.Lswa_w_last:
	s_bitcmp1_b32 s58, 0
	s_cbranch_scc1 .Lswa_w_last_odd
	s_waitcnt vmcnt(1)
	ds_write_b128 v32, v[152:155]
	s_waitcnt vmcnt(0)
	ds_write_b128 v33, v[156:159] offset:9216
	s_branch .LBB0_1377
.Lswa_w_last_odd:
	s_waitcnt vmcnt(1)
	ds_write_b128 v32, v[64:67]
	s_waitcnt vmcnt(0)
	ds_write_b128 v33, v[68:71] offset:9216
	s_branch .LBB0_1377
